# prep phase: DPP moves instead of LDS permutes for the 8-lane row sums of the K copies; compression maximum combined per workgroup
# baseline (speedup 1.0000x reference)
; DI void phase_prep(const Args& a, int layer, LAS unsigned char* lds) {
;     ...
;             if (which >= 3) {
;                 const int srccol = (which == 3 ? C_KS : which == 4 ? C_KW : C_KB) + g * 64;
;                 bf16_t* dst = (bf16_t*)(ws + (which == 3 ? WS_KSF : which == 4 ? WS_KWF : WS_KBF)) + (size_t)bg * 64 * S + (size_t)st * 4096;
;                 float rmax = 0.f;
; #pragma unroll
;                 for (int i = 0; i < 8; ++i) { const int tok = i * 8 + (lane >> 3), q = lane & 7;
;                     const u32x4 v = *(const u32x4*)(P + (size_t)(b * S + st * 64 + tok) * NP + srccol + q * 8);
;                     const int pos = which == 3 ? (((tok >> 4) * 2 + (q >> 2)) * 64 + (q & 3) * 16 + (tok & 15))
;                                                : ((tok >> 5) * 256 + (q >> 1) * 64 + (q & 1) * 32 + (tok & 31));
;                     *(u32x4*)(dst + pos * 8) = v;
;                     float ss = bflo(v.x) * bflo(v.x) + bfhi(v.x) * bfhi(v.x) + bflo(v.y) * bflo(v.y) + bfhi(v.y) * bfhi(v.y)
;                              + bflo(v.z) * bflo(v.z) + bfhi(v.z) * bfhi(v.z) + bflo(v.w) * bflo(v.w) + bfhi(v.w) * bfhi(v.w);
;                     ss += __shfl_xor(ss, 1); ss += __shfl_xor(ss, 2); ss += __shfl_xor(ss, 4);
;                     rmax = fmaxf(rmax, ss); }
;                 rmax = fmaxf(rmax, __shfl_xor(rmax, 8)); rmax = fmaxf(rmax, __shfl_xor(rmax, 16)); rmax = fmaxf(rmax, __shfl_xor(rmax, 32));
;                 if (lane == 0) atomicMax((unsigned*)(ws + WS_KMAX) + (layer * 4 + (which - 3)) * 4 + bg, __builtin_bit_cast(unsigned, rmax));
.LBB0_349:
	s_andn2_saveexec_b64 s[42:43], s[42:43]
	s_cbranch_execz .LBB0_346
	v_and_b32_e32 v1, 0x7ffffc00, v52
	s_movk_i32 s0, 0xc00
	v_cmp_eq_u32_e64 s[38:39], s0, v1
	v_cmp_eq_u32_e64 s[0:1], s26, v1
	v_mov_b32_e32 v3, v129
	v_cndmask_b32_e64 v59, v21, v37, s[38:39]
	v_cndmask_b32_e64 v1, v208, v209, s[0:1]
	v_cndmask_b32_e64 v13, v1, v210, s[38:39]
	v_cndmask_b32_e64 v1, v211, v212, s[0:1]
	v_cndmask_b32_e64 v128, v1, v213, s[38:39]
	v_lshl_add_u64 v[10:11], s[98:99], 0, v[128:129]
	v_lshl_add_u64 v[2:3], v[10:11], 0, v[2:3]
	v_mov_b32_e32 v1, v129
	v_lshl_add_u64 v[10:11], v[2:3], 0, v[0:1]
	v_and_b32_e32 v3, 64, v197
	v_xor_b32_e32 v2, 1, v197
	v_add_u32_e32 v54, 64, v3
	v_cmp_lt_i32_e64 s[0:1], v2, v54
	v_lshlrev_b32_e32 v0, 1, v13
	v_lshl_or_b32 v128, v12, 7, v0
	v_cndmask_b32_e64 v2, v197, v2, s[0:1]
	v_lshlrev_b32_e32 v57, 2, v2
	v_xor_b32_e32 v2, 2, v197
	v_cmp_lt_i32_e64 s[0:1], v2, v54
	v_lshl_add_u64 v[0:1], v[6:7], 0, v[128:129]
	v_or_b32_e32 v68, v58, v17
	v_mul_u32_u24_e32 v68, 0xd00, v68
	v_lshlrev_b32_e32 v68, 1, v68
	v_mov_b32_e32 v69, v129
	v_lshl_add_u64 v[68:69], v[0:1], 0, v[68:69]
	global_load_dwordx4 v[70:73], v[68:69], off
	v_or_b32_e32 v68, v58, v22
	v_mul_u32_u24_e32 v68, 0xd00, v68
	v_lshlrev_b32_e32 v68, 1, v68
	v_mov_b32_e32 v69, v129
	v_lshl_add_u64 v[68:69], v[0:1], 0, v[68:69]
	global_load_dwordx4 v[74:77], v[68:69], off
	v_or_b32_e32 v68, v58, v23
	v_mul_u32_u24_e32 v68, 0xd00, v68
	v_lshlrev_b32_e32 v68, 1, v68
	v_mov_b32_e32 v69, v129
	v_lshl_add_u64 v[68:69], v[0:1], 0, v[68:69]
	global_load_dwordx4 v[78:81], v[68:69], off
	v_or_b32_e32 v68, v58, v24
	v_mul_u32_u24_e32 v68, 0xd00, v68
	v_lshlrev_b32_e32 v68, 1, v68
	v_mov_b32_e32 v69, v129
	v_lshl_add_u64 v[68:69], v[0:1], 0, v[68:69]
	global_load_dwordx4 v[82:85], v[68:69], off
	v_or_b32_e32 v68, v58, v25
	v_mul_u32_u24_e32 v68, 0xd00, v68
	v_lshlrev_b32_e32 v68, 1, v68
	v_mov_b32_e32 v69, v129
	v_lshl_add_u64 v[68:69], v[0:1], 0, v[68:69]
	global_load_dwordx4 v[86:89], v[68:69], off
	v_or_b32_e32 v68, v58, v26
	v_mul_u32_u24_e32 v68, 0xd00, v68
	v_lshlrev_b32_e32 v68, 1, v68
	v_mov_b32_e32 v69, v129
	v_lshl_add_u64 v[68:69], v[0:1], 0, v[68:69]
	global_load_dwordx4 v[90:93], v[68:69], off
	v_or_b32_e32 v68, v58, v27
	v_mul_u32_u24_e32 v68, 0xd00, v68
	v_lshlrev_b32_e32 v68, 1, v68
	v_mov_b32_e32 v69, v129
	v_lshl_add_u64 v[68:69], v[0:1], 0, v[68:69]
	global_load_dwordx4 v[94:97], v[68:69], off
	v_or_b32_e32 v68, v58, v28
	v_mul_u32_u24_e32 v68, 0xd00, v68
	v_lshlrev_b32_e32 v68, 1, v68
	v_mov_b32_e32 v69, v129
	v_lshl_add_u64 v[68:69], v[0:1], 0, v[68:69]
	global_load_dwordx4 v[98:101], v[68:69], off
	s_waitcnt vmcnt(0)
	v_or_b32_e32 v12, v59, v17
	v_cndmask_b32_e64 v2, v197, v2, s[0:1]
	v_lshlrev_b32_e32 v56, 2, v2
	v_xor_b32_e32 v2, 4, v197
	v_cmp_lt_i32_e64 s[0:1], v2, v54
	s_nop 1
	v_cndmask_b32_e64 v2, v197, v2, s[0:1]
	v_lshlrev_b32_e32 v55, 2, v2
	v_or_b32_e32 v2, v58, v17
	v_mul_u32_u24_e32 v2, 0xd00, v2
	v_lshlrev_b32_e32 v128, 1, v2
	v_lshl_add_u64 v[2:3], v[0:1], 0, v[128:129]
	v_mov_b64_e32 v[60:61], v[70:71]
	v_mov_b64_e32 v[62:63], v[72:73]
	v_lshlrev_b32_e32 v128, 4, v12
	v_lshl_add_u64 v[12:13], v[10:11], 0, v[128:129]
	s_mov_b32 s0, 0x34000
	v_add_co_u32_e64 v2, s[0:1], s0, v2
	global_store_dwordx4 v[12:13], v[60:63], off
	v_lshlrev_b32_e32 v64, 16, v60
	s_nop 0
	v_and_b32_e32 v60, 0xffff0000, v60
	v_mul_f32_e32 v60, v60, v60
	v_fmac_f32_e32 v60, v64, v64
	v_lshlrev_b32_e32 v64, 16, v61
	v_fmac_f32_e32 v60, v64, v64
	v_and_b32_e32 v61, 0xffff0000, v61
	v_fmac_f32_e32 v60, v61, v61
	v_lshlrev_b32_e32 v61, 16, v62
	v_fmac_f32_e32 v60, v61, v61
	v_and_b32_e32 v61, 0xffff0000, v62
	v_fmac_f32_e32 v60, v61, v61
	v_lshlrev_b32_e32 v61, 16, v63
	v_fmac_f32_e32 v60, v61, v61
	v_and_b32_e32 v61, 0xffff0000, v63
	v_fmac_f32_e32 v60, v61, v61
	s_nop 1
	v_mov_b32_dpp v61, v60 quad_perm:[1,0,3,2] row_mask:0xf bank_mask:0xf
	v_or_b32_e32 v64, v59, v22
	v_addc_co_u32_e64 v3, s[0:1], 0, v3, s[0:1]
	s_waitcnt lgkmcnt(0)
	v_add_f32_e32 v60, v60, v61
	s_nop 1
	v_mov_b32_dpp v61, v60 quad_perm:[2,3,0,1] row_mask:0xf bank_mask:0xf
	s_waitcnt lgkmcnt(0)
	v_add_f32_e32 v60, v60, v61
	s_nop 1
	v_mov_b32_dpp v61, v60 row_half_mirror row_mask:0xf bank_mask:0xf
	s_waitcnt lgkmcnt(0)
	v_add_f32_e32 v66, v60, v61
	v_or_b32_e32 v60, v58, v22
	v_mul_u32_u24_e32 v60, 0xd00, v60
	v_lshlrev_b32_e32 v128, 1, v60
	v_lshl_add_u64 v[60:61], v[0:1], 0, v[128:129]
	v_mov_b64_e32 v[60:61], v[74:75]
	v_mov_b64_e32 v[62:63], v[76:77]
	v_lshlrev_b32_e32 v128, 4, v64
	v_lshl_add_u64 v[64:65], v[10:11], 0, v[128:129]
	global_store_dwordx4 v[64:65], v[60:63], off
	v_lshlrev_b32_e32 v64, 16, v60
	s_nop 0
	v_and_b32_e32 v60, 0xffff0000, v60
	v_mul_f32_e32 v60, v60, v60
	v_fmac_f32_e32 v60, v64, v64
	v_lshlrev_b32_e32 v64, 16, v61
	v_fmac_f32_e32 v60, v64, v64
	v_and_b32_e32 v61, 0xffff0000, v61
	v_fmac_f32_e32 v60, v61, v61
	v_lshlrev_b32_e32 v61, 16, v62
	v_fmac_f32_e32 v60, v61, v61
	v_and_b32_e32 v61, 0xffff0000, v62
	v_fmac_f32_e32 v60, v61, v61
	v_lshlrev_b32_e32 v61, 16, v63
	v_fmac_f32_e32 v60, v61, v61
	v_and_b32_e32 v61, 0xffff0000, v63
	v_fmac_f32_e32 v60, v61, v61
	s_nop 1
	v_mov_b32_dpp v61, v60 quad_perm:[1,0,3,2] row_mask:0xf bank_mask:0xf
	v_cndmask_b32_e64 v64, v38, v39, s[38:39]
	s_waitcnt lgkmcnt(0)
	v_add_f32_e32 v60, v60, v61
	s_nop 1
	v_mov_b32_dpp v61, v60 quad_perm:[2,3,0,1] row_mask:0xf bank_mask:0xf
	s_waitcnt lgkmcnt(0)
	v_add_f32_e32 v60, v60, v61
	s_nop 1
	v_mov_b32_dpp v61, v60 row_half_mirror row_mask:0xf bank_mask:0xf
	s_waitcnt lgkmcnt(0)
; DI void phase_prep(const Args& a, int layer, LAS unsigned char* lds) {
;     ...
;             if (which >= 3) {
;                 const int srccol = (which == 3 ? C_KS : which == 4 ? C_KW : C_KB) + g * 64;
;                 bf16_t* dst = (bf16_t*)(ws + (which == 3 ? WS_KSF : which == 4 ? WS_KWF : WS_KBF)) + (size_t)bg * 64 * S + (size_t)st * 4096;
;                 float rmax = 0.f;
; #pragma unroll
;                 for (int i = 0; i < 8; ++i) { const int tok = i * 8 + (lane >> 3), q = lane & 7;
;                     const u32x4 v = *(const u32x4*)(P + (size_t)(b * S + st * 64 + tok) * NP + srccol + q * 8);
;                     const int pos = which == 3 ? (((tok >> 4) * 2 + (q >> 2)) * 64 + (q & 3) * 16 + (tok & 15))
;                                                : ((tok >> 5) * 256 + (q >> 1) * 64 + (q & 1) * 32 + (tok & 31));
;                     *(u32x4*)(dst + pos * 8) = v;
;                     float ss = bflo(v.x) * bflo(v.x) + bfhi(v.x) * bfhi(v.x) + bflo(v.y) * bflo(v.y) + bfhi(v.y) * bfhi(v.y)
;                              + bflo(v.z) * bflo(v.z) + bfhi(v.z) * bfhi(v.z) + bflo(v.w) * bflo(v.w) + bfhi(v.w) * bfhi(v.w);
;                     ss += __shfl_xor(ss, 1); ss += __shfl_xor(ss, 2); ss += __shfl_xor(ss, 4);
;                     rmax = fmaxf(rmax, ss); }
;                 rmax = fmaxf(rmax, __shfl_xor(rmax, 8)); rmax = fmaxf(rmax, __shfl_xor(rmax, 16)); rmax = fmaxf(rmax, __shfl_xor(rmax, 32));
;                 if (lane == 0) atomicMax((unsigned*)(ws + WS_KMAX) + (layer * 4 + (which - 3)) * 4 + bg, __builtin_bit_cast(unsigned, rmax));
	v_add_f32_e32 v60, v60, v61
	v_max3_f32 v66, v66, 0, v60
	v_or_b32_e32 v60, v58, v23
	v_mul_u32_u24_e32 v60, 0xd00, v60
	v_lshlrev_b32_e32 v128, 1, v60
	v_lshl_add_u64 v[60:61], v[0:1], 0, v[128:129]
	v_mov_b64_e32 v[60:61], v[78:79]
	v_mov_b64_e32 v[62:63], v[80:81]
	v_lshlrev_b32_e32 v128, 4, v64
	v_lshl_add_u64 v[64:65], v[10:11], 0, v[128:129]
	global_store_dwordx4 v[64:65], v[60:63], off
	v_lshlrev_b32_e32 v64, 16, v60
	s_nop 0
	v_and_b32_e32 v60, 0xffff0000, v60
	v_mul_f32_e32 v60, v60, v60
	v_fmac_f32_e32 v60, v64, v64
	v_lshlrev_b32_e32 v64, 16, v61
	v_fmac_f32_e32 v60, v64, v64
	v_and_b32_e32 v61, 0xffff0000, v61
	v_fmac_f32_e32 v60, v61, v61
	v_lshlrev_b32_e32 v61, 16, v62
	v_fmac_f32_e32 v60, v61, v61
	v_and_b32_e32 v61, 0xffff0000, v62
	v_fmac_f32_e32 v60, v61, v61
	v_lshlrev_b32_e32 v61, 16, v63
	v_fmac_f32_e32 v60, v61, v61
	v_and_b32_e32 v61, 0xffff0000, v63
	v_fmac_f32_e32 v60, v61, v61
	s_nop 1
	v_mov_b32_dpp v61, v60 quad_perm:[1,0,3,2] row_mask:0xf bank_mask:0xf
	v_cndmask_b32_e64 v64, v40, v41, s[38:39]
	s_waitcnt lgkmcnt(0)
	v_add_f32_e32 v60, v60, v61
	s_nop 1
	v_mov_b32_dpp v61, v60 quad_perm:[2,3,0,1] row_mask:0xf bank_mask:0xf
	s_waitcnt lgkmcnt(0)
	v_add_f32_e32 v60, v60, v61
	s_nop 1
	v_mov_b32_dpp v61, v60 row_half_mirror row_mask:0xf bank_mask:0xf
	s_waitcnt lgkmcnt(0)
	v_add_f32_e32 v67, v60, v61
	v_or_b32_e32 v60, v58, v24
	v_mul_u32_u24_e32 v60, 0xd00, v60
	v_lshlrev_b32_e32 v128, 1, v60
	v_lshl_add_u64 v[60:61], v[0:1], 0, v[128:129]
	v_mov_b64_e32 v[60:61], v[82:83]
	v_mov_b64_e32 v[62:63], v[84:85]
	v_lshlrev_b32_e32 v128, 4, v64
	v_lshl_add_u64 v[64:65], v[10:11], 0, v[128:129]
	global_store_dwordx4 v[64:65], v[60:63], off
	v_lshlrev_b32_e32 v64, 16, v60
	s_nop 0
	v_and_b32_e32 v60, 0xffff0000, v60
	v_mul_f32_e32 v60, v60, v60
	v_fmac_f32_e32 v60, v64, v64
	v_lshlrev_b32_e32 v64, 16, v61
	v_fmac_f32_e32 v60, v64, v64
	v_and_b32_e32 v61, 0xffff0000, v61
	v_fmac_f32_e32 v60, v61, v61
	v_lshlrev_b32_e32 v61, 16, v62
	v_fmac_f32_e32 v60, v61, v61
	v_and_b32_e32 v61, 0xffff0000, v62
	v_fmac_f32_e32 v60, v61, v61
	v_lshlrev_b32_e32 v61, 16, v63
	v_fmac_f32_e32 v60, v61, v61
	v_and_b32_e32 v61, 0xffff0000, v63
	v_mov_b64_e32 v[62:63], v[86:87]
	v_mov_b64_e32 v[64:65], v[88:89]
	v_add_co_u32_e64 v2, s[0:1], s26, v12
	v_fmac_f32_e32 v60, v61, v61
	s_nop 0
	v_addc_co_u32_e64 v3, s[0:1], 0, v13, s[0:1]
	s_nop 1
	v_mov_b32_dpp v61, v60 quad_perm:[1,0,3,2] row_mask:0xf bank_mask:0xf
	s_waitcnt lgkmcnt(0)
	v_add_f32_e32 v60, v60, v61
	s_nop 1
	v_mov_b32_dpp v61, v60 quad_perm:[2,3,0,1] row_mask:0xf bank_mask:0xf
	s_waitcnt lgkmcnt(0)
	v_add_f32_e32 v60, v60, v61
	s_nop 1
	v_mov_b32_dpp v61, v60 row_half_mirror row_mask:0xf bank_mask:0xf
	s_waitcnt lgkmcnt(0)
	v_add_f32_e32 v60, v60, v61
	v_max3_f32 v60, v66, v67, v60
	global_store_dwordx4 v[2:3], v[62:65], off
	v_and_b32_e32 v3, 0xffff0000, v62
	v_lshlrev_b32_e32 v2, 16, v62
	v_mul_f32_e32 v3, v3, v3
	v_fmac_f32_e32 v3, v2, v2
	v_lshlrev_b32_e32 v2, 16, v63
	v_fmac_f32_e32 v3, v2, v2
	v_and_b32_e32 v2, 0xffff0000, v63
	v_fmac_f32_e32 v3, v2, v2
	v_lshlrev_b32_e32 v2, 16, v64
	v_fmac_f32_e32 v3, v2, v2
	v_and_b32_e32 v2, 0xffff0000, v64
	v_fmac_f32_e32 v3, v2, v2
	v_lshlrev_b32_e32 v2, 16, v65
	v_fmac_f32_e32 v3, v2, v2
	v_and_b32_e32 v2, 0xffff0000, v65
	v_fmac_f32_e32 v3, v2, v2
	s_nop 1
	v_mov_b32_dpp v2, v3 quad_perm:[1,0,3,2] row_mask:0xf bank_mask:0xf
	s_waitcnt lgkmcnt(0)
	v_add_f32_e32 v2, v3, v2
	s_nop 1
	v_mov_b32_dpp v3, v2 quad_perm:[2,3,0,1] row_mask:0xf bank_mask:0xf
	s_waitcnt lgkmcnt(0)
	v_add_f32_e32 v2, v2, v3
	s_nop 1
	v_mov_b32_dpp v3, v2 row_half_mirror row_mask:0xf bank_mask:0xf
	s_waitcnt lgkmcnt(0)
	v_add_f32_e32 v12, v2, v3
	v_or_b32_e32 v2, v58, v26
	v_mul_u32_u24_e32 v2, 0xd00, v2
	v_lshlrev_b32_e32 v128, 1, v2
	v_lshl_add_u64 v[2:3], v[0:1], 0, v[128:129]
	v_mov_b64_e32 v[62:63], v[90:91]
	v_mov_b64_e32 v[64:65], v[92:93]
	v_or_b32_e32 v2, v59, v46
	v_lshlrev_b32_e32 v128, 4, v2
	v_lshl_add_u64 v[2:3], v[10:11], 0, v[128:129]
	v_add_co_u32_e64 v2, s[0:1], s26, v2
	s_nop 1
	v_addc_co_u32_e64 v3, s[0:1], 0, v3, s[0:1]
	global_store_dwordx4 v[2:3], v[62:65], off
	v_and_b32_e32 v3, 0xffff0000, v62
	v_lshlrev_b32_e32 v2, 16, v62
	v_mul_f32_e32 v3, v3, v3
	v_fmac_f32_e32 v3, v2, v2
	v_lshlrev_b32_e32 v2, 16, v63
	v_fmac_f32_e32 v3, v2, v2
	v_and_b32_e32 v2, 0xffff0000, v63
	v_fmac_f32_e32 v3, v2, v2
	v_lshlrev_b32_e32 v2, 16, v64
	v_fmac_f32_e32 v3, v2, v2
	v_and_b32_e32 v2, 0xffff0000, v64
	v_fmac_f32_e32 v3, v2, v2
	v_lshlrev_b32_e32 v2, 16, v65
	v_fmac_f32_e32 v3, v2, v2
	v_and_b32_e32 v2, 0xffff0000, v65
	v_fmac_f32_e32 v3, v2, v2
	s_nop 1
	v_mov_b32_dpp v2, v3 quad_perm:[1,0,3,2] row_mask:0xf bank_mask:0xf
	s_waitcnt lgkmcnt(0)
; DI void phase_prep(const Args& a, int layer, LAS unsigned char* lds) {
;     ...
;                     float ss = bflo(v.x) * bflo(v.x) + bfhi(v.x) * bfhi(v.x) + bflo(v.y) * bflo(v.y) + bfhi(v.y) * bfhi(v.y)
;                              + bflo(v.z) * bflo(v.z) + bfhi(v.z) * bfhi(v.z) + bflo(v.w) * bflo(v.w) + bfhi(v.w) * bfhi(v.w);
;                     ss += __shfl_xor(ss, 1); ss += __shfl_xor(ss, 2); ss += __shfl_xor(ss, 4);
;                     rmax = fmaxf(rmax, ss); }
;                 rmax = fmaxf(rmax, __shfl_xor(rmax, 8)); rmax = fmaxf(rmax, __shfl_xor(rmax, 16)); rmax = fmaxf(rmax, __shfl_xor(rmax, 32));
;                 if (lane == 0) atomicMax((unsigned*)(ws + WS_KMAX) + (layer * 4 + (which - 3)) * 4 + bg, __builtin_bit_cast(unsigned, rmax));
	v_add_f32_e32 v2, v3, v2
	s_nop 1
	v_mov_b32_dpp v3, v2 quad_perm:[2,3,0,1] row_mask:0xf bank_mask:0xf
	s_waitcnt lgkmcnt(0)
	v_add_f32_e32 v2, v2, v3
	s_nop 1
	v_mov_b32_dpp v3, v2 row_half_mirror row_mask:0xf bank_mask:0xf
	s_waitcnt lgkmcnt(0)
	v_add_f32_e32 v2, v2, v3
	v_max3_f32 v12, v60, v12, v2
	v_or_b32_e32 v2, v58, v27
	v_mul_u32_u24_e32 v2, 0xd00, v2
	v_lshlrev_b32_e32 v128, 1, v2
	v_lshl_add_u64 v[2:3], v[0:1], 0, v[128:129]
	v_mov_b64_e32 v[60:61], v[94:95]
	v_mov_b64_e32 v[62:63], v[96:97]
	v_cndmask_b32_e64 v2, v47, v48, s[38:39]
	v_lshlrev_b32_e32 v128, 4, v2
	v_lshl_add_u64 v[2:3], v[10:11], 0, v[128:129]
	global_store_dwordx4 v[2:3], v[60:63], off
	v_and_b32_e32 v3, 0xffff0000, v60
	v_lshlrev_b32_e32 v2, 16, v60
	v_mul_f32_e32 v3, v3, v3
	v_fmac_f32_e32 v3, v2, v2
	v_lshlrev_b32_e32 v2, 16, v61
	v_fmac_f32_e32 v3, v2, v2
	v_and_b32_e32 v2, 0xffff0000, v61
	v_fmac_f32_e32 v3, v2, v2
	v_lshlrev_b32_e32 v2, 16, v62
	v_fmac_f32_e32 v3, v2, v2
	v_and_b32_e32 v2, 0xffff0000, v62
	v_fmac_f32_e32 v3, v2, v2
	v_lshlrev_b32_e32 v2, 16, v63
	v_fmac_f32_e32 v3, v2, v2
	v_and_b32_e32 v2, 0xffff0000, v63
	v_fmac_f32_e32 v3, v2, v2
	s_nop 1
	v_mov_b32_dpp v2, v3 quad_perm:[1,0,3,2] row_mask:0xf bank_mask:0xf
	s_waitcnt lgkmcnt(0)
	v_add_f32_e32 v2, v3, v2
	s_nop 1
	v_mov_b32_dpp v3, v2 quad_perm:[2,3,0,1] row_mask:0xf bank_mask:0xf
	s_waitcnt lgkmcnt(0)
	v_add_f32_e32 v2, v2, v3
	s_nop 1
	v_mov_b32_dpp v3, v2 row_half_mirror row_mask:0xf bank_mask:0xf
	s_waitcnt lgkmcnt(0)
	v_add_f32_e32 v13, v2, v3
	v_or_b32_e32 v2, v58, v28
	v_mul_u32_u24_e32 v2, 0xd00, v2
	v_lshlrev_b32_e32 v128, 1, v2
	v_lshl_add_u64 v[0:1], v[0:1], 0, v[128:129]
	v_mov_b64_e32 v[0:1], v[98:99]
	v_mov_b64_e32 v[2:3], v[100:101]
	v_cndmask_b32_e64 v58, v49, v50, s[38:39]
	v_lshlrev_b32_e32 v128, 4, v58
	v_lshl_add_u64 v[10:11], v[10:11], 0, v[128:129]
	global_store_dwordx4 v[10:11], v[0:3], off
	v_lshlrev_b32_e32 v10, 16, v0
	s_nop 0
	v_and_b32_e32 v0, 0xffff0000, v0
	v_mul_f32_e32 v0, v0, v0
	v_fmac_f32_e32 v0, v10, v10
	v_lshlrev_b32_e32 v10, 16, v1
	v_fmac_f32_e32 v0, v10, v10
	v_and_b32_e32 v1, 0xffff0000, v1
	v_fmac_f32_e32 v0, v1, v1
	v_lshlrev_b32_e32 v1, 16, v2
	v_fmac_f32_e32 v0, v1, v1
	v_and_b32_e32 v1, 0xffff0000, v2
	v_fmac_f32_e32 v0, v1, v1
	v_lshlrev_b32_e32 v1, 16, v3
	v_fmac_f32_e32 v0, v1, v1
	v_and_b32_e32 v1, 0xffff0000, v3
	v_fmac_f32_e32 v0, v1, v1
	s_nop 1
	v_mov_b32_dpp v1, v0 quad_perm:[1,0,3,2] row_mask:0xf bank_mask:0xf
	s_waitcnt lgkmcnt(0)
	v_add_f32_e32 v0, v0, v1
	s_nop 1
	v_mov_b32_dpp v1, v0 quad_perm:[2,3,0,1] row_mask:0xf bank_mask:0xf
	s_waitcnt lgkmcnt(0)
	v_add_f32_e32 v0, v0, v1
	s_nop 1
	v_mov_b32_dpp v1, v0 row_half_mirror row_mask:0xf bank_mask:0xf
	s_waitcnt lgkmcnt(0)
	v_add_f32_e32 v0, v0, v1
	v_xor_b32_e32 v1, 8, v197
	v_cmp_lt_i32_e64 s[0:1], v1, v54
	v_max3_f32 v0, v12, v13, v0
	s_nop 0
	v_cndmask_b32_e64 v1, v197, v1, s[0:1]
	v_lshlrev_b32_e32 v1, 2, v1
	ds_bpermute_b32 v1, v1, v0
	s_waitcnt lgkmcnt(0)
	v_max_f32_e32 v1, v1, v1
	v_max_f32_e32 v0, v0, v1
	v_xor_b32_e32 v1, 16, v197
	v_cmp_lt_i32_e64 s[0:1], v1, v54
	s_nop 1
	v_cndmask_b32_e64 v1, v197, v1, s[0:1]
	v_lshlrev_b32_e32 v1, 2, v1
	ds_bpermute_b32 v1, v1, v0
	s_waitcnt lgkmcnt(0)
	v_max_f32_e32 v1, v1, v1
	v_max_f32_e32 v0, v0, v1
	v_xor_b32_e32 v1, 32, v197
	v_cmp_lt_i32_e64 s[0:1], v1, v54
	s_nop 1
	v_cndmask_b32_e64 v1, v197, v1, s[0:1]
	v_lshlrev_b32_e32 v1, 2, v1
	ds_bpermute_b32 v1, v1, v0
	s_and_saveexec_b64 s[0:1], vcc
	s_cbranch_execz .LBB0_345
	v_lshrrev_b32_e32 v2, 22, v53
	v_add_u32_e32 v2, v52, v2
	v_ashrrev_i32_e32 v2, 10, v2
	s_waitcnt lgkmcnt(0)
	v_max_f32_e32 v1, v1, v1
	v_max_f32_e32 v0, v0, v0
	v_max_f32_e32 v3, v0, v1
	v_lshl_add_u32 v0, v2, 2, s8
	v_readlane_b32 s16, v252, 42
	v_ashrrev_i32_e32 v1, 31, v0
	v_readlane_b32 s17, v252, 43
	v_lshlrev_b32_e32 v128, 2, v9
	s_nop 0
	v_lshl_add_u64 v[0:1], v[0:1], 2, s[16:17]
	v_lshl_add_u64 v[0:1], v[0:1], 0, v[128:129]
	v_lshrrev_b32_e32 v2, 6, v185
	v_lshl_add_u32 v2, v2, 2, s44
	ds_write_b32 v2, v3
	s_waitcnt lgkmcnt(0)
	s_barrier
	s_mov_b32 s46, s44
	s_xor_b32 s44, s44, 32
	v_readfirstlane_b32 s45, v185
	s_nop 1
	s_lshr_b32 s45, s45, 6
	s_cmp_lg_u32 s45, 0
	s_cbranch_scc1 .LBB0_345
	v_mov_b32_e32 v2, s46
	ds_read_b128 v[108:111], v2
	ds_read_b128 v[112:115], v2 offset:16
	s_waitcnt lgkmcnt(0)
	v_max3_u32 v3, v108, v109, v110
	v_max3_u32 v3, v3, v111, v112
	v_max3_u32 v3, v3, v113, v114
	v_max_u32_e32 v3, v3, v115
	global_atomic_umax v[0:1], v3, off
	s_branch .LBB0_345

; DI unsigned pk2(float lo, float hi) { const f32x2 v = {lo, hi}; return __builtin_bit_cast(unsigned, __builtin_convertvector(v, bf16v2)); }
; DI void phase_prep(const Args& a, int layer, LAS unsigned char* lds) {
;     ...
;                 if (kv == 0) {
;                     u32x4 w; w.x = pk2(o[0], o[1]); w.y = pk2(o[2], o[3]); w.z = pk2(o[4], o[5]); w.w = pk2(o[6], o[7]);
;                     float ss = bflo(w.x) * bflo(w.x) + bfhi(w.x) * bfhi(w.x) + bflo(w.y) * bflo(w.y) + bfhi(w.y) * bfhi(w.y)
;                              + bflo(w.z) * bflo(w.z) + bfhi(w.z) * bfhi(w.z) + bflo(w.w) * bflo(w.w) + bfhi(w.w) * bfhi(w.w);
;                     ss += __shfl_xor(ss, 1); ss += __shfl_xor(ss, 2); ss += __shfl_xor(ss, 4);
;                     ss = fmaxf(ss, __shfl_xor(ss, 8)); ss = fmaxf(ss, __shfl_xor(ss, 16)); ss = fmaxf(ss, __shfl_xor(ss, 32));
;                     if (lane == 0) atomicMax((unsigned*)(ws + WS_KMAX) + (layer * 4 + 3) * 4 + bg, __builtin_bit_cast(unsigned, ss));
.LBB0_403:
	s_ff1_i32_b64 s17, s[22:23]
	v_readlane_b32 s43, v6, s17
	s_lshl_b64 s[44:45], 1, s17
	s_max_u32 s42, s42, s43
	s_andn2_b64 s[22:23], s[22:23], s[44:45]
	s_cmp_lg_u64 s[22:23], 0
	s_cbranch_scc1 .LBB0_403
	v_mbcnt_lo_u32_b32 v6, exec_lo, 0
	v_mbcnt_hi_u32_b32 v6, exec_hi, v6
	v_cmp_eq_u32_e32 vcc, 0, v6
	s_and_saveexec_b64 s[22:23], vcc
	s_xor_b64 s[22:23], exec, s[22:23]
	s_cbranch_execz .LBB0_392
	s_lshl_b32 s16, s16, 2
	v_mov_b32_e32 v6, s16
	v_mov_b32_e32 v7, s42
	v_lshrrev_b32_e32 v108, 6, v185
	v_lshlrev_b32_e32 v108, 2, v108
	v_add_u32_e32 v108, 0x20040, v108
	ds_write_b32 v108, v7
	s_waitcnt lgkmcnt(0)
	s_barrier
	v_readfirstlane_b32 s49, v185
	s_nop 1
	s_lshr_b32 s49, s49, 6
	s_cmp_lg_u32 s49, 0
	s_cbranch_scc1 .LBB0_392
	v_mov_b32_e32 v107, 0x20040
	ds_read_b128 v[108:111], v107
	ds_read_b128 v[112:115], v107 offset:16
	s_waitcnt lgkmcnt(0)
	v_max3_u32 v7, v108, v109, v110
	v_max3_u32 v7, v7, v111, v112
	v_max3_u32 v7, v7, v113, v114
	v_max_u32_e32 v7, v7, v115
	global_atomic_umax v6, v7, s[40:41]
	s_branch .LBB0_392
